# SPLIT-ACQ-HOIST: split-tile exchange of GEMM2/GEMM4 issues its acquire invalidate when polling starts instead of after the poll (on STAGGER-P2)
# speedup vs baseline: 1.0033x; 1.0033x over previous
.LBB0_1079:
	s_or_b64 exec, exec, s[30:31]
	s_and_b32 s30, s3, 1
	s_cmp_lg_u32 s47, s30
	s_cbranch_scc1 .LBB0_1089
	v_mov_b32_e32 v130, 0x3fffff
	buffer_inv sc1
	s_branch .LBB0_1082

.LBB0_1084:
	s_add_i32 s47, s3, 1
	s_cmp_gt_u32 s3, 1
	s_mov_b64 s[30:31], -1
	s_cbranch_scc0 .LBB0_1086
	s_and_b32 s31, s47, 3
	s_lshl_b32 s30, s72, 2
	s_or_b32 s31, s31, s30
	s_mul_i32 s31, s31, 0x18000
	s_add_i32 s31, s31, s45
	s_add_i32 s49, s31, 0x10000
	buffer_load_dwordx4 v[138:141], v193, s[8:11], s49 offen
	s_add_i32 s49, s31, 0x10400
	buffer_load_dwordx4 v[142:145], v193, s[8:11], s49 offen
	s_add_i32 s49, s31, 0x10800
	buffer_load_dwordx4 v[146:149], v193, s[8:11], s49 offen
	s_add_i32 s49, s31, 0x10c00
	buffer_load_dwordx4 v[150:153], v193, s[8:11], s49 offen
	s_add_i32 s49, s31, 0x11000
	buffer_load_dwordx4 v[154:157], v193, s[8:11], s49 offen
	s_add_i32 s49, s31, 0x11400
	buffer_load_dwordx4 v[158:161], v193, s[8:11], s49 offen
	s_add_i32 s49, s31, 0x11800
	s_add_i32 s31, s31, 0x11c00
	buffer_load_dwordx4 v[134:137], v193, s[8:11], s49 offen
	buffer_load_dwordx4 v[130:133], v193, s[8:11], s31 offen
	s_or_b32 s31, s3, s30
	s_xor_b32 s31, s31, 2
	s_mul_i32 s31, s31, 0x18000
	s_add_i32 s31, s31, s45
	s_add_i32 s49, s31, 0x8000
	s_waitcnt vmcnt(7)
	v_cvt_f32_f16_e32 v164, v140
	v_cvt_f32_f16_sdwa v165, v140 dst_sel:DWORD dst_unused:UNUSED_PAD src0_sel:WORD_1
	v_cvt_f32_f16_e32 v140, v141
	v_cvt_f32_f16_sdwa v141, v141 dst_sel:DWORD dst_unused:UNUSED_PAD src0_sel:WORD_1
	s_waitcnt vmcnt(6)
	v_cvt_f32_f16_e32 v198, v142
	v_cvt_f32_f16_sdwa v199, v142 dst_sel:DWORD dst_unused:UNUSED_PAD src0_sel:WORD_1
	v_cvt_f32_f16_e32 v142, v143
	v_cvt_f32_f16_sdwa v143, v143 dst_sel:DWORD dst_unused:UNUSED_PAD src0_sel:WORD_1
	v_cvt_f32_f16_e32 v210, v144
	v_cvt_f32_f16_sdwa v211, v144 dst_sel:DWORD dst_unused:UNUSED_PAD src0_sel:WORD_1
	v_cvt_f32_f16_e32 v144, v145
	v_cvt_f32_f16_sdwa v145, v145 dst_sel:DWORD dst_unused:UNUSED_PAD src0_sel:WORD_1
	s_waitcnt vmcnt(5)
	v_cvt_f32_f16_e32 v212, v146
	v_cvt_f32_f16_sdwa v213, v146 dst_sel:DWORD dst_unused:UNUSED_PAD src0_sel:WORD_1
	v_cvt_f32_f16_e32 v146, v147
	v_cvt_f32_f16_sdwa v147, v147 dst_sel:DWORD dst_unused:UNUSED_PAD src0_sel:WORD_1
	v_cvt_f32_f16_e32 v214, v148
	v_cvt_f32_f16_sdwa v215, v148 dst_sel:DWORD dst_unused:UNUSED_PAD src0_sel:WORD_1
	v_cvt_f32_f16_e32 v148, v149
	v_cvt_f32_f16_sdwa v149, v149 dst_sel:DWORD dst_unused:UNUSED_PAD src0_sel:WORD_1
	s_waitcnt vmcnt(4)
	v_cvt_f32_f16_e32 v216, v150
	v_cvt_f32_f16_sdwa v217, v150 dst_sel:DWORD dst_unused:UNUSED_PAD src0_sel:WORD_1
	v_cvt_f32_f16_e32 v150, v151
	v_cvt_f32_f16_sdwa v151, v151 dst_sel:DWORD dst_unused:UNUSED_PAD src0_sel:WORD_1
	v_cvt_f32_f16_e32 v218, v152
	v_cvt_f32_f16_sdwa v219, v152 dst_sel:DWORD dst_unused:UNUSED_PAD src0_sel:WORD_1
	v_cvt_f32_f16_e32 v152, v153
	v_cvt_f32_f16_sdwa v153, v153 dst_sel:DWORD dst_unused:UNUSED_PAD src0_sel:WORD_1
	s_waitcnt vmcnt(3)
	v_cvt_f32_f16_e32 v220, v154
	v_cvt_f32_f16_sdwa v221, v154 dst_sel:DWORD dst_unused:UNUSED_PAD src0_sel:WORD_1
	v_cvt_f32_f16_e32 v154, v155
	v_cvt_f32_f16_sdwa v155, v155 dst_sel:DWORD dst_unused:UNUSED_PAD src0_sel:WORD_1
	v_cvt_f32_f16_e32 v222, v156
	v_cvt_f32_f16_sdwa v223, v156 dst_sel:DWORD dst_unused:UNUSED_PAD src0_sel:WORD_1
	v_cvt_f32_f16_e32 v156, v157
	v_cvt_f32_f16_sdwa v157, v157 dst_sel:DWORD dst_unused:UNUSED_PAD src0_sel:WORD_1
	v_cvt_f32_f16_e32 v162, v138
	v_cvt_f32_f16_sdwa v163, v138 dst_sel:DWORD dst_unused:UNUSED_PAD src0_sel:WORD_1
	v_cvt_f32_f16_e32 v138, v139
	v_cvt_f32_f16_sdwa v139, v139 dst_sel:DWORD dst_unused:UNUSED_PAD src0_sel:WORD_1
	v_pk_add_f32 v[124:125], v[124:125], v[140:141]
	v_pk_add_f32 v[120:121], v[120:121], v[142:143]
	v_pk_add_f32 v[140:141], v[116:117], v[144:145]
	v_pk_add_f32 v[144:145], v[112:113], v[146:147]
	v_pk_add_f32 v[142:143], v[110:111], v[212:213]
	v_pk_add_f32 v[148:149], v[108:109], v[148:149]
	v_pk_add_f32 v[146:147], v[106:107], v[214:215]
	v_pk_add_f32 v[112:113], v[104:105], v[150:151]
	v_pk_add_f32 v[110:111], v[102:103], v[216:217]
	v_pk_add_f32 v[108:109], v[100:101], v[152:153]
	v_pk_add_f32 v[106:107], v[98:99], v[218:219]
	v_pk_add_f32 v[100:101], v[96:97], v[154:155]
	v_pk_add_f32 v[98:99], v[94:95], v[220:221]
	v_pk_add_f32 v[104:105], v[92:93], v[156:157]
	v_pk_add_f32 v[102:103], v[90:91], v[222:223]
	s_waitcnt vmcnt(1)
	v_cvt_f32_f16_e32 v90, v134
	v_cvt_f32_f16_sdwa v91, v134 dst_sel:DWORD dst_unused:UNUSED_PAD src0_sel:WORD_1
	v_cvt_f32_f16_e32 v92, v135
	v_cvt_f32_f16_sdwa v93, v135 dst_sel:DWORD dst_unused:UNUSED_PAD src0_sel:WORD_1
	v_cvt_f32_f16_e32 v94, v136
	v_cvt_f32_f16_e32 v96, v137
	v_cvt_f32_f16_sdwa v97, v137 dst_sel:DWORD dst_unused:UNUSED_PAD src0_sel:WORD_1
	v_cvt_f32_f16_sdwa v95, v136 dst_sel:DWORD dst_unused:UNUSED_PAD src0_sel:WORD_1
	v_pk_add_f32 v[128:129], v[128:129], v[138:139]
	v_pk_add_f32 v[126:127], v[126:127], v[162:163]
	v_pk_add_f32 v[122:123], v[122:123], v[164:165]
	v_cvt_f32_f16_e32 v224, v158
	v_cvt_f32_f16_sdwa v225, v158 dst_sel:DWORD dst_unused:UNUSED_PAD src0_sel:WORD_1
	v_cvt_f32_f16_e32 v158, v159
	v_cvt_f32_f16_sdwa v159, v159 dst_sel:DWORD dst_unused:UNUSED_PAD src0_sel:WORD_1
	v_cvt_f32_f16_e32 v226, v160
	v_cvt_f32_f16_sdwa v227, v160 dst_sel:DWORD dst_unused:UNUSED_PAD src0_sel:WORD_1
	v_cvt_f32_f16_e32 v160, v161
	v_cvt_f32_f16_sdwa v161, v161 dst_sel:DWORD dst_unused:UNUSED_PAD src0_sel:WORD_1
	v_pk_add_f32 v[118:119], v[118:119], v[198:199]
	v_pk_add_f32 v[138:139], v[114:115], v[210:211]
	v_pk_add_f32 v[80:81], v[80:81], v[92:93]
	v_pk_add_f32 v[78:79], v[78:79], v[90:91]
	v_pk_add_f32 v[76:77], v[76:77], v[96:97]
	v_pk_add_f32 v[74:75], v[74:75], v[94:95]
	s_waitcnt vmcnt(0)
	v_cvt_f32_f16_e32 v90, v130
	v_cvt_f32_f16_sdwa v91, v130 dst_sel:DWORD dst_unused:UNUSED_PAD src0_sel:WORD_1
	v_cvt_f32_f16_e32 v92, v131
	v_cvt_f32_f16_sdwa v93, v131 dst_sel:DWORD dst_unused:UNUSED_PAD src0_sel:WORD_1
	v_cvt_f32_f16_e32 v94, v132
	v_cvt_f32_f16_e32 v96, v133
	v_cvt_f32_f16_sdwa v97, v133 dst_sel:DWORD dst_unused:UNUSED_PAD src0_sel:WORD_1
	v_cvt_f32_f16_sdwa v95, v132 dst_sel:DWORD dst_unused:UNUSED_PAD src0_sel:WORD_1
	v_pk_add_f32 v[88:89], v[88:89], v[158:159]
	v_pk_add_f32 v[86:87], v[86:87], v[224:225]
	v_pk_add_f32 v[84:85], v[84:85], v[160:161]
	v_pk_add_f32 v[82:83], v[82:83], v[226:227]
	v_pk_add_f32 v[72:73], v[72:73], v[92:93]
	v_pk_add_f32 v[70:71], v[70:71], v[90:91]
	v_pk_add_f32 v[68:69], v[68:69], v[96:97]
	v_pk_add_f32 v[66:67], v[66:67], v[94:95]
	s_nop 0
	buffer_load_dwordx4 v[90:93], v193, s[8:11], s49 offen
	s_add_i32 s49, s31, 0x8400
	buffer_load_dwordx4 v[94:97], v193, s[8:11], s49 offen
	s_add_i32 s49, s31, 0x8800
	buffer_load_dwordx4 v[134:137], v193, s[8:11], s49 offen
	s_add_i32 s49, s31, 0x8c00
	buffer_load_dwordx4 v[154:157], v193, s[8:11], s49 offen
	s_add_i32 s49, s31, 0x9000
	buffer_load_dwordx4 v[210:213], v193, s[8:11], s49 offen
	s_add_i32 s49, s31, 0x9400
	buffer_load_dwordx4 v[214:217], v193, s[8:11], s49 offen
	s_add_i32 s49, s31, 0x9800
	s_add_i32 s31, s31, 0x9c00
	buffer_load_dwordx4 v[130:133], v193, s[8:11], s49 offen
	buffer_load_dwordx4 v[114:117], v193, s[8:11], s31 offen
	s_add_i32 s31, s3, -1
	s_and_b32 s31, s31, 3
	s_or_b32 s30, s31, s30
	s_mul_i32 s30, s30, 0x18000
	s_add_i32 s30, s45, s30
	s_or_b32 s31, s30, 0x400
	s_waitcnt vmcnt(7)
	v_cvt_f32_f16_e32 v150, v90
	v_cvt_f32_f16_sdwa v151, v90 dst_sel:DWORD dst_unused:UNUSED_PAD src0_sel:WORD_1
	v_cvt_f32_f16_e32 v90, v91
	v_cvt_f32_f16_sdwa v91, v91 dst_sel:DWORD dst_unused:UNUSED_PAD src0_sel:WORD_1
	v_cvt_f32_f16_e32 v152, v92
	v_cvt_f32_f16_sdwa v153, v92 dst_sel:DWORD dst_unused:UNUSED_PAD src0_sel:WORD_1
	s_waitcnt vmcnt(6)
	v_cvt_f32_f16_e32 v198, v94
	v_cvt_f32_f16_sdwa v199, v94 dst_sel:DWORD dst_unused:UNUSED_PAD src0_sel:WORD_1
	v_cvt_f32_f16_e32 v94, v95
	v_cvt_f32_f16_sdwa v95, v95 dst_sel:DWORD dst_unused:UNUSED_PAD src0_sel:WORD_1
	v_cvt_f32_f16_e32 v218, v96
	v_cvt_f32_f16_sdwa v219, v96 dst_sel:DWORD dst_unused:UNUSED_PAD src0_sel:WORD_1
	v_cvt_f32_f16_e32 v96, v97
	v_cvt_f32_f16_sdwa v97, v97 dst_sel:DWORD dst_unused:UNUSED_PAD src0_sel:WORD_1
	v_cvt_f32_f16_e32 v92, v93
	v_cvt_f32_f16_sdwa v93, v93 dst_sel:DWORD dst_unused:UNUSED_PAD src0_sel:WORD_1
	s_waitcnt vmcnt(4)
	v_cvt_f32_f16_e32 v224, v154
	v_cvt_f32_f16_sdwa v225, v154 dst_sel:DWORD dst_unused:UNUSED_PAD src0_sel:WORD_1
	v_pk_add_f32 v[164:165], v[128:129], v[90:91]
	v_pk_add_f32 v[158:159], v[122:123], v[152:153]
	v_pk_add_f32 v[152:153], v[120:121], v[94:95]
	v_pk_add_f32 v[120:121], v[140:141], v[96:97]
	v_cvt_f32_f16_e32 v90, v155
	v_cvt_f32_f16_sdwa v91, v155 dst_sel:DWORD dst_unused:UNUSED_PAD src0_sel:WORD_1
	v_cvt_f32_f16_e32 v94, v156
	v_cvt_f32_f16_e32 v96, v157
	v_cvt_f32_f16_sdwa v97, v157 dst_sel:DWORD dst_unused:UNUSED_PAD src0_sel:WORD_1
	v_cvt_f32_f16_sdwa v95, v156 dst_sel:DWORD dst_unused:UNUSED_PAD src0_sel:WORD_1
	v_pk_add_f32 v[160:161], v[124:125], v[92:93]
	v_pk_add_f32 v[92:93], v[112:113], v[90:91]
	v_pk_add_f32 v[90:91], v[110:111], v[224:225]
	v_pk_add_f32 v[96:97], v[108:109], v[96:97]
	v_pk_add_f32 v[94:95], v[106:107], v[94:95]
	s_waitcnt vmcnt(3)
	v_cvt_f32_f16_e32 v106, v210
	v_cvt_f32_f16_sdwa v107, v210 dst_sel:DWORD dst_unused:UNUSED_PAD src0_sel:WORD_1
	v_cvt_f32_f16_e32 v108, v211
	v_cvt_f32_f16_sdwa v109, v211 dst_sel:DWORD dst_unused:UNUSED_PAD src0_sel:WORD_1
	v_cvt_f32_f16_e32 v110, v212
	v_cvt_f32_f16_e32 v112, v213
	v_cvt_f32_f16_sdwa v113, v213 dst_sel:DWORD dst_unused:UNUSED_PAD src0_sel:WORD_1
	v_cvt_f32_f16_sdwa v111, v212 dst_sel:DWORD dst_unused:UNUSED_PAD src0_sel:WORD_1
	v_pk_add_f32 v[100:101], v[100:101], v[108:109]
	v_pk_add_f32 v[98:99], v[98:99], v[106:107]
	v_pk_add_f32 v[104:105], v[104:105], v[112:113]
	v_pk_add_f32 v[102:103], v[102:103], v[110:111]
	s_waitcnt vmcnt(2)
	v_cvt_f32_f16_e32 v106, v214
	v_cvt_f32_f16_sdwa v107, v214 dst_sel:DWORD dst_unused:UNUSED_PAD src0_sel:WORD_1
	v_cvt_f32_f16_e32 v108, v215
	v_cvt_f32_f16_sdwa v109, v215 dst_sel:DWORD dst_unused:UNUSED_PAD src0_sel:WORD_1
	v_cvt_f32_f16_e32 v110, v216
	v_cvt_f32_f16_e32 v112, v217
	v_cvt_f32_f16_sdwa v113, v217 dst_sel:DWORD dst_unused:UNUSED_PAD src0_sel:WORD_1
	v_cvt_f32_f16_sdwa v111, v216 dst_sel:DWORD dst_unused:UNUSED_PAD src0_sel:WORD_1
	v_cvt_f32_f16_e32 v220, v134
	v_cvt_f32_f16_sdwa v221, v134 dst_sel:DWORD dst_unused:UNUSED_PAD src0_sel:WORD_1
	v_cvt_f32_f16_e32 v134, v135
	v_cvt_f32_f16_sdwa v135, v135 dst_sel:DWORD dst_unused:UNUSED_PAD src0_sel:WORD_1
	v_cvt_f32_f16_e32 v222, v136
	v_cvt_f32_f16_sdwa v223, v136 dst_sel:DWORD dst_unused:UNUSED_PAD src0_sel:WORD_1
	v_cvt_f32_f16_e32 v136, v137
	v_cvt_f32_f16_sdwa v137, v137 dst_sel:DWORD dst_unused:UNUSED_PAD src0_sel:WORD_1
	v_pk_add_f32 v[108:109], v[88:89], v[108:109]
	v_pk_add_f32 v[106:107], v[86:87], v[106:107]
	v_pk_add_f32 v[112:113], v[84:85], v[112:113]
	v_pk_add_f32 v[110:111], v[82:83], v[110:111]
	s_waitcnt vmcnt(1)
	v_cvt_f32_f16_e32 v82, v130
	v_cvt_f32_f16_sdwa v83, v130 dst_sel:DWORD dst_unused:UNUSED_PAD src0_sel:WORD_1
	v_cvt_f32_f16_e32 v84, v131
	v_cvt_f32_f16_sdwa v85, v131 dst_sel:DWORD dst_unused:UNUSED_PAD src0_sel:WORD_1
	v_cvt_f32_f16_e32 v86, v132
	v_cvt_f32_f16_e32 v88, v133
	v_cvt_f32_f16_sdwa v89, v133 dst_sel:DWORD dst_unused:UNUSED_PAD src0_sel:WORD_1
	v_cvt_f32_f16_sdwa v87, v132 dst_sel:DWORD dst_unused:UNUSED_PAD src0_sel:WORD_1
	v_pk_add_f32 v[162:163], v[126:127], v[150:151]
	v_pk_add_f32 v[150:151], v[118:119], v[198:199]
	v_pk_add_f32 v[118:119], v[138:139], v[218:219]
	v_pk_add_f32 v[128:129], v[144:145], v[134:135]
	v_pk_add_f32 v[126:127], v[142:143], v[220:221]
	v_pk_add_f32 v[124:125], v[148:149], v[136:137]
	v_pk_add_f32 v[122:123], v[146:147], v[222:223]
	v_pk_add_f32 v[80:81], v[80:81], v[84:85]
	v_pk_add_f32 v[78:79], v[78:79], v[82:83]
	v_pk_add_f32 v[76:77], v[76:77], v[88:89]
	v_pk_add_f32 v[74:75], v[74:75], v[86:87]
	s_waitcnt vmcnt(0)
	v_cvt_f32_f16_e32 v82, v114
	v_cvt_f32_f16_sdwa v83, v114 dst_sel:DWORD dst_unused:UNUSED_PAD src0_sel:WORD_1
	v_cvt_f32_f16_e32 v84, v115
	v_cvt_f32_f16_sdwa v85, v115 dst_sel:DWORD dst_unused:UNUSED_PAD src0_sel:WORD_1
	v_cvt_f32_f16_e32 v86, v116
	v_cvt_f32_f16_e32 v88, v117
	v_cvt_f32_f16_sdwa v89, v117 dst_sel:DWORD dst_unused:UNUSED_PAD src0_sel:WORD_1
	v_cvt_f32_f16_sdwa v87, v116 dst_sel:DWORD dst_unused:UNUSED_PAD src0_sel:WORD_1
	v_pk_add_f32 v[136:137], v[72:73], v[84:85]
	v_pk_add_f32 v[134:135], v[70:71], v[82:83]
	v_pk_add_f32 v[140:141], v[68:69], v[88:89]
	v_pk_add_f32 v[138:139], v[66:67], v[86:87]
	s_nop 0
	buffer_load_dwordx4 v[66:69], v193, s[8:11], s30 offen
	buffer_load_dwordx4 v[70:73], v193, s[8:11], s31 offen
	s_or_b32 s31, s30, 0x800
	buffer_load_dwordx4 v[82:85], v193, s[8:11], s31 offen
	s_or_b32 s31, s30, 0xc00
	buffer_load_dwordx4 v[210:213], v193, s[8:11], s31 offen
	s_or_b32 s31, s30, 0x1000
	buffer_load_dwordx4 v[214:217], v193, s[8:11], s31 offen
	s_or_b32 s31, s30, 0x1400
	buffer_load_dwordx4 v[218:221], v193, s[8:11], s31 offen
	s_or_b32 s31, s30, 0x1800
	s_or_b32 s30, s30, 0x1c00
	buffer_load_dwordx4 v[154:157], v193, s[8:11], s31 offen
	buffer_load_dwordx4 v[146:149], v193, s[8:11], s30 offen
	s_mov_b64 s[30:31], 0
	s_waitcnt vmcnt(7)
	v_cvt_f32_f16_e32 v86, v66
	v_cvt_f32_f16_sdwa v87, v66 dst_sel:DWORD dst_unused:UNUSED_PAD src0_sel:WORD_1
	v_cvt_f32_f16_e32 v66, v67
	v_cvt_f32_f16_sdwa v67, v67 dst_sel:DWORD dst_unused:UNUSED_PAD src0_sel:WORD_1
	v_cvt_f32_f16_e32 v88, v68
	v_cvt_f32_f16_e32 v114, v69
	v_cvt_f32_f16_sdwa v115, v69 dst_sel:DWORD dst_unused:UNUSED_PAD src0_sel:WORD_1
	v_cvt_f32_f16_sdwa v89, v68 dst_sel:DWORD dst_unused:UNUSED_PAD src0_sel:WORD_1
	s_waitcnt vmcnt(6)
	v_cvt_f32_f16_e32 v68, v71
	v_cvt_f32_f16_sdwa v69, v71 dst_sel:DWORD dst_unused:UNUSED_PAD src0_sel:WORD_1
	v_pk_add_f32 v[144:145], v[164:165], v[66:67]
	v_cvt_f32_f16_e32 v66, v70
	v_cvt_f32_f16_sdwa v67, v70 dst_sel:DWORD dst_unused:UNUSED_PAD src0_sel:WORD_1
	v_cvt_f32_f16_e32 v70, v72
	v_cvt_f32_f16_sdwa v71, v72 dst_sel:DWORD dst_unused:UNUSED_PAD src0_sel:WORD_1
	v_pk_add_f32 v[116:117], v[152:153], v[68:69]
	s_waitcnt vmcnt(5)
	v_cvt_f32_f16_e32 v68, v83
	v_cvt_f32_f16_sdwa v69, v83 dst_sel:DWORD dst_unused:UNUSED_PAD src0_sel:WORD_1
	v_pk_add_f32 v[142:143], v[162:163], v[86:87]
	v_pk_add_f32 v[132:133], v[160:161], v[114:115]
	v_cvt_f32_f16_e32 v86, v73
	v_cvt_f32_f16_sdwa v87, v73 dst_sel:DWORD dst_unused:UNUSED_PAD src0_sel:WORD_1
	v_pk_add_f32 v[114:115], v[150:151], v[66:67]
	v_pk_add_f32 v[118:119], v[118:119], v[70:71]
	v_cvt_f32_f16_e32 v66, v82
	v_cvt_f32_f16_sdwa v67, v82 dst_sel:DWORD dst_unused:UNUSED_PAD src0_sel:WORD_1
	v_cvt_f32_f16_e32 v70, v84
	v_cvt_f32_f16_e32 v72, v85
	v_cvt_f32_f16_sdwa v73, v85 dst_sel:DWORD dst_unused:UNUSED_PAD src0_sel:WORD_1
	v_cvt_f32_f16_sdwa v71, v84 dst_sel:DWORD dst_unused:UNUSED_PAD src0_sel:WORD_1
	v_pk_add_f32 v[84:85], v[128:129], v[68:69]
	s_waitcnt vmcnt(4)
	v_cvt_f32_f16_e32 v68, v211
	v_cvt_f32_f16_sdwa v69, v211 dst_sel:DWORD dst_unused:UNUSED_PAD src0_sel:WORD_1
	v_pk_add_f32 v[130:131], v[158:159], v[88:89]
	v_pk_add_f32 v[120:121], v[120:121], v[86:87]
	v_pk_add_f32 v[82:83], v[126:127], v[66:67]
	v_pk_add_f32 v[88:89], v[124:125], v[72:73]
	v_pk_add_f32 v[86:87], v[122:123], v[70:71]
	v_cvt_f32_f16_e32 v66, v210
	v_cvt_f32_f16_sdwa v67, v210 dst_sel:DWORD dst_unused:UNUSED_PAD src0_sel:WORD_1
	v_cvt_f32_f16_e32 v70, v212
	v_cvt_f32_f16_e32 v72, v213
	v_cvt_f32_f16_sdwa v73, v213 dst_sel:DWORD dst_unused:UNUSED_PAD src0_sel:WORD_1
	v_cvt_f32_f16_sdwa v71, v212 dst_sel:DWORD dst_unused:UNUSED_PAD src0_sel:WORD_1
	v_pk_add_f32 v[68:69], v[92:93], v[68:69]
	s_waitcnt vmcnt(3)
	v_cvt_f32_f16_e32 v92, v215
	v_cvt_f32_f16_sdwa v93, v215 dst_sel:DWORD dst_unused:UNUSED_PAD src0_sel:WORD_1
	v_pk_add_f32 v[66:67], v[90:91], v[66:67]
	v_pk_add_f32 v[72:73], v[96:97], v[72:73]
	v_pk_add_f32 v[70:71], v[94:95], v[70:71]
	v_cvt_f32_f16_e32 v90, v214
	v_cvt_f32_f16_sdwa v91, v214 dst_sel:DWORD dst_unused:UNUSED_PAD src0_sel:WORD_1
	v_cvt_f32_f16_e32 v94, v216
	v_cvt_f32_f16_e32 v96, v217
	v_cvt_f32_f16_sdwa v97, v217 dst_sel:DWORD dst_unused:UNUSED_PAD src0_sel:WORD_1
	v_cvt_f32_f16_sdwa v95, v216 dst_sel:DWORD dst_unused:UNUSED_PAD src0_sel:WORD_1
	v_pk_add_f32 v[152:153], v[100:101], v[92:93]
	s_waitcnt vmcnt(2)
	v_cvt_f32_f16_e32 v92, v219
	v_cvt_f32_f16_sdwa v93, v219 dst_sel:DWORD dst_unused:UNUSED_PAD src0_sel:WORD_1
	v_pk_add_f32 v[150:151], v[98:99], v[90:91]
	v_pk_add_f32 v[160:161], v[104:105], v[96:97]
	v_pk_add_f32 v[158:159], v[102:103], v[94:95]
	v_cvt_f32_f16_e32 v90, v218
	v_cvt_f32_f16_sdwa v91, v218 dst_sel:DWORD dst_unused:UNUSED_PAD src0_sel:WORD_1
	v_cvt_f32_f16_e32 v94, v220
	v_cvt_f32_f16_e32 v96, v221
	v_cvt_f32_f16_sdwa v97, v221 dst_sel:DWORD dst_unused:UNUSED_PAD src0_sel:WORD_1
	v_cvt_f32_f16_sdwa v95, v220 dst_sel:DWORD dst_unused:UNUSED_PAD src0_sel:WORD_1
	v_pk_add_f32 v[124:125], v[108:109], v[92:93]
	s_waitcnt vmcnt(1)
	v_cvt_f32_f16_e32 v92, v155
	v_cvt_f32_f16_sdwa v93, v155 dst_sel:DWORD dst_unused:UNUSED_PAD src0_sel:WORD_1
	v_pk_add_f32 v[122:123], v[106:107], v[90:91]
	v_pk_add_f32 v[128:129], v[112:113], v[96:97]
	v_pk_add_f32 v[126:127], v[110:111], v[94:95]
	v_cvt_f32_f16_e32 v90, v154
	v_cvt_f32_f16_sdwa v91, v154 dst_sel:DWORD dst_unused:UNUSED_PAD src0_sel:WORD_1
	v_cvt_f32_f16_e32 v94, v156
	v_cvt_f32_f16_e32 v96, v157
	v_cvt_f32_f16_sdwa v97, v157 dst_sel:DWORD dst_unused:UNUSED_PAD src0_sel:WORD_1
	v_cvt_f32_f16_sdwa v95, v156 dst_sel:DWORD dst_unused:UNUSED_PAD src0_sel:WORD_1
	v_pk_add_f32 v[104:105], v[80:81], v[92:93]
	s_waitcnt vmcnt(0)
	v_cvt_f32_f16_e32 v80, v149
	v_cvt_f32_f16_sdwa v81, v149 dst_sel:DWORD dst_unused:UNUSED_PAD src0_sel:WORD_1
	v_pk_add_f32 v[102:103], v[78:79], v[90:91]
	v_pk_add_f32 v[112:113], v[76:77], v[96:97]
	v_pk_add_f32 v[110:111], v[74:75], v[94:95]
	v_cvt_f32_f16_e32 v74, v146
	v_cvt_f32_f16_sdwa v75, v146 dst_sel:DWORD dst_unused:UNUSED_PAD src0_sel:WORD_1
	v_cvt_f32_f16_e32 v76, v147
	v_cvt_f32_f16_sdwa v77, v147 dst_sel:DWORD dst_unused:UNUSED_PAD src0_sel:WORD_1
	v_cvt_f32_f16_e32 v78, v148
	v_cvt_f32_f16_sdwa v79, v148 dst_sel:DWORD dst_unused:UNUSED_PAD src0_sel:WORD_1
	v_pk_add_f32 v[80:81], v[140:141], v[80:81]
	v_add_u32_e32 v140, 0x80, v192
	v_ashrrev_i32_e32 v141, 31, v140
	v_pk_add_f32 v[76:77], v[136:137], v[76:77]
	v_pk_add_f32 v[74:75], v[134:135], v[74:75]
	v_pk_add_f32 v[78:79], v[138:139], v[78:79]
	v_lshl_add_u64 v[134:135], v[196:197], 2, s[12:13]
	v_lshlrev_b64 v[90:91], 12, v[140:141]
	v_lshl_add_u64 v[148:149], v[134:135], 0, v[90:91]
	global_load_dwordx4 v[106:109], v[194:195], off
	global_load_dwordx4 v[98:101], v[194:195], off offset:64
	global_load_dwordx4 v[94:97], v[194:195], off offset:512
	global_load_dwordx4 v[90:93], v[194:195], off offset:576
	s_mov_b64 s[78:79], 0x10000
	v_mov_b32_e32 v250, v148
	v_mov_b32_e32 v251, v149
	global_load_dwordx4 v[210:213], v[250:251], off
	global_load_dwordx4 v[214:217], v[250:251], off offset:64
	global_load_dwordx4 v[218:221], v[250:251], off offset:512
	global_load_dwordx4 v[222:225], v[250:251], off offset:576
	v_lshl_add_u64 v[250:251], v[250:251], 0, s[78:79]
	global_load_dwordx4 v[226:229], v[250:251], off
	global_load_dwordx4 v[230:233], v[250:251], off offset:64
	global_load_dwordx4 v[234:237], v[250:251], off offset:512
	global_load_dwordx4 v[238:241], v[250:251], off offset:576
	v_lshl_add_u64 v[250:251], v[250:251], 0, s[78:79]
	global_load_dwordx4 v[242:245], v[250:251], off
	global_load_dwordx4 v[246:249], v[250:251], off offset:64
	v_and_b32_e32 v146, 1, v1
	v_add_u32_e32 v147, 12, v209
	v_cmp_eq_u32_e32 vcc, 0, v146
	s_waitcnt vmcnt(9)
	s_nop 1
	v_mov_b32_e32 v136, v210
	v_mov_b32_e32 v137, v211
	v_mov_b32_e32 v138, v212
	v_mov_b32_e32 v139, v213
	s_nop 1
	v_pk_fma_f32 v[136:137], v[142:143], v[106:107], v[136:137]
	v_pk_fma_f32 v[144:145], v[144:145], v[108:109], v[138:139]
	s_waitcnt vmcnt(8)
	s_nop 1
	v_mov_b32_e32 v154, v214
	v_mov_b32_e32 v155, v215
	v_mov_b32_e32 v156, v216
	v_mov_b32_e32 v157, v217
	global_load_dwordx4 v[210:213], v[250:251], off offset:512
	global_load_dwordx4 v[214:217], v[250:251], off offset:576
	s_nop 1
	v_pk_fma_f32 v[130:131], v[130:131], v[98:99], v[154:155]
	v_cvt_pk_bf16_f32 v136, v136, v137
	v_cvt_pk_bf16_f32 v138, v130, v131
	v_pk_fma_f32 v[132:133], v[132:133], v[100:101], v[156:157]
	v_cvt_pk_bf16_f32 v137, v144, v145
	v_cndmask_b32_e32 v146, v147, v209, vcc
	v_add_u32_e32 v146, v146, v208
	v_ashrrev_i32_e32 v147, 31, v146
	v_cvt_pk_bf16_f32 v139, v132, v133
	v_lshlrev_b64 v[130:131], 11, v[140:141]
	v_lshl_add_u64 v[132:133], v[176:177], 0, v[130:131]
	v_lshlrev_b64 v[130:131], 1, v[146:147]
	v_permlane16_swap_b32_e32 v136, v138
	v_permlane16_swap_b32_e32 v137, v139
	v_lshl_add_u64 v[132:133], v[132:133], 0, v[130:131]
	global_store_dwordx4 v[132:133], v[136:139], off
	s_nop 0
	s_waitcnt vmcnt(10)
	s_nop 1
	v_mov_b32_e32 v136, v218
	v_mov_b32_e32 v137, v219
	v_mov_b32_e32 v138, v220
	v_mov_b32_e32 v139, v221
	s_nop 1
	v_pk_fma_f32 v[138:139], v[152:153], v[96:97], v[138:139]
	v_pk_fma_f32 v[136:137], v[150:151], v[94:95], v[136:137]
	s_waitcnt vmcnt(9)
	s_nop 1
	v_mov_b32_e32 v140, v222
	v_mov_b32_e32 v141, v223
	v_mov_b32_e32 v142, v224
	v_mov_b32_e32 v143, v225
	v_lshl_add_u64 v[250:251], v[250:251], 0, s[78:79]
	global_load_dwordx4 v[218:221], v[250:251], off
	global_load_dwordx4 v[222:225], v[250:251], off offset:64
	s_nop 1
	v_pk_fma_f32 v[142:143], v[160:161], v[92:93], v[142:143]
	v_pk_fma_f32 v[140:141], v[158:159], v[90:91], v[140:141]
	v_cvt_pk_bf16_f32 v136, v136, v137
	v_cvt_pk_bf16_f32 v137, v138, v139
	v_cvt_pk_bf16_f32 v138, v140, v141
	v_cvt_pk_bf16_f32 v139, v142, v143
	s_nop 0
	v_permlane16_swap_b32_e32 v136, v138
	v_permlane16_swap_b32_e32 v137, v139
	global_store_dwordx4 v[132:133], v[136:139], off offset:256
	v_add_u32_e32 v132, 0x90, v192
	v_ashrrev_i32_e32 v133, 31, v132
	v_lshlrev_b64 v[136:137], 12, v[132:133]
	v_lshl_add_u64 v[144:145], v[134:135], 0, v[136:137]
	v_lshlrev_b64 v[132:133], 11, v[132:133]
	v_lshl_add_u64 v[132:133], v[176:177], 0, v[132:133]
	v_lshl_add_u64 v[132:133], v[132:133], 0, v[130:131]
	s_waitcnt vmcnt(11)
	s_nop 1
	v_mov_b32_e32 v136, v226
	v_mov_b32_e32 v137, v227
	v_mov_b32_e32 v138, v228
	v_mov_b32_e32 v139, v229
	s_nop 1
	v_pk_fma_f32 v[116:117], v[116:117], v[108:109], v[138:139]
	v_pk_fma_f32 v[114:115], v[114:115], v[106:107], v[136:137]
	s_waitcnt vmcnt(10)
	s_nop 1
	v_mov_b32_e32 v140, v230
	v_mov_b32_e32 v141, v231
	v_mov_b32_e32 v142, v232
	v_mov_b32_e32 v143, v233
	global_load_dwordx4 v[226:229], v[250:251], off offset:512
	global_load_dwordx4 v[230:233], v[250:251], off offset:576
	s_nop 1
	v_pk_fma_f32 v[120:121], v[120:121], v[100:101], v[142:143]
	v_pk_fma_f32 v[118:119], v[118:119], v[98:99], v[140:141]
	v_bfe_u32 v140, v116, 16, 1
	v_bfe_u32 v141, v117, 16, 1
	v_add3_u32 v116, v116, v140, s66
	v_add3_u32 v117, v117, v141, s66
	v_lshrrev_b32_e32 v136, 16, v116
	v_cvt_pk_bf16_f32 v114, v114, v115
	v_cvt_pk_bf16_f32 v116, v118, v119
	v_and_or_b32 v115, v117, s67, v136
	v_cvt_pk_bf16_f32 v117, v120, v121
	v_permlane16_swap_b32_e32 v114, v116
	s_nop 0
	v_permlane16_swap_b32_e32 v115, v117
	global_store_dwordx4 v[132:133], v[114:117], off
	s_nop 0
	v_add_u32_e32 v136, 0xa0, v192
	v_ashrrev_i32_e32 v137, 31, v136
	v_lshlrev_b64 v[138:139], 12, v[136:137]
	v_lshl_add_u64 v[138:139], v[134:135], 0, v[138:139]
	s_waitcnt vmcnt(12)
	s_nop 1
	v_mov_b32_e32 v114, v234
	v_mov_b32_e32 v115, v235
	v_mov_b32_e32 v116, v236
	v_mov_b32_e32 v117, v237
	s_nop 1
	v_pk_fma_f32 v[116:117], v[124:125], v[96:97], v[116:117]
	v_pk_fma_f32 v[114:115], v[122:123], v[94:95], v[114:115]
	s_waitcnt vmcnt(11)
	s_nop 1
	v_mov_b32_e32 v118, v238
	v_mov_b32_e32 v119, v239
	v_mov_b32_e32 v120, v240
	v_mov_b32_e32 v121, v241
	s_nop 1
	v_pk_fma_f32 v[120:121], v[128:129], v[92:93], v[120:121]
	v_pk_fma_f32 v[118:119], v[126:127], v[90:91], v[118:119]
	v_bfe_u32 v126, v116, 16, 1
	v_bfe_u32 v127, v117, 16, 1
	v_add3_u32 v116, v116, v126, s66
	v_add3_u32 v117, v117, v127, s66
	v_lshrrev_b32_e32 v122, 16, v116
	v_cvt_pk_bf16_f32 v114, v114, v115
	v_cvt_pk_bf16_f32 v116, v118, v119
	v_and_or_b32 v115, v117, s67, v122
	v_cvt_pk_bf16_f32 v117, v120, v121
	v_permlane16_swap_b32_e32 v114, v116
	s_nop 0
	v_permlane16_swap_b32_e32 v115, v117
	global_store_dwordx4 v[132:133], v[114:117], off offset:256
	s_nop 0
	v_lshlrev_b64 v[122:123], 11, v[136:137]
	v_lshl_add_u64 v[122:123], v[176:177], 0, v[122:123]
	v_lshl_add_u64 v[122:123], v[122:123], 0, v[130:131]
	s_waitcnt vmcnt(11)
	s_nop 1
	v_mov_b32_e32 v114, v242
	v_mov_b32_e32 v115, v243
	v_mov_b32_e32 v116, v244
	v_mov_b32_e32 v117, v245
	s_nop 1
	v_pk_fma_f32 v[84:85], v[84:85], v[108:109], v[116:117]
	v_pk_fma_f32 v[82:83], v[82:83], v[106:107], v[114:115]
	s_waitcnt vmcnt(10)
	s_nop 1
	v_mov_b32_e32 v118, v246
	v_mov_b32_e32 v119, v247
	v_mov_b32_e32 v120, v248
	v_mov_b32_e32 v121, v249
	s_nop 1
	v_pk_fma_f32 v[88:89], v[88:89], v[100:101], v[120:121]
	v_pk_fma_f32 v[86:87], v[86:87], v[98:99], v[118:119]
	v_bfe_u32 v118, v84, 16, 1
	v_bfe_u32 v120, v88, 16, 1
	v_bfe_u32 v119, v85, 16, 1
	v_bfe_u32 v121, v89, 16, 1
	v_add3_u32 v84, v84, v118, s66
	v_add3_u32 v88, v88, v120, s66
	v_add3_u32 v85, v85, v119, s66
	v_add3_u32 v89, v89, v121, s66
	v_lshrrev_b32_e32 v114, 16, v84
	v_lshrrev_b32_e32 v88, 16, v88
	v_cvt_pk_bf16_f32 v82, v82, v83
	v_cvt_pk_bf16_f32 v84, v86, v87
	v_and_or_b32 v83, v85, s67, v114
	v_and_or_b32 v85, v89, s67, v88
	v_permlane16_swap_b32_e32 v82, v84
	s_nop 0
	v_permlane16_swap_b32_e32 v83, v85
	global_store_dwordx4 v[122:123], v[82:85], off
	s_nop 0
	v_add_u32_e32 v114, 0xb0, v192
	v_ashrrev_i32_e32 v115, 31, v114
	v_lshlrev_b64 v[116:117], 12, v[114:115]
	v_lshl_add_u64 v[116:117], v[134:135], 0, v[116:117]
	v_lshlrev_b64 v[138:139], 10, v[114:115]
	s_waitcnt vmcnt(10)
	s_nop 1
	v_mov_b32_e32 v82, v210
	v_mov_b32_e32 v83, v211
	v_mov_b32_e32 v84, v212
	v_mov_b32_e32 v85, v213
	s_nop 1
	v_pk_fma_f32 v[84:85], v[104:105], v[96:97], v[84:85]
	v_pk_fma_f32 v[82:83], v[102:103], v[94:95], v[82:83]
	s_waitcnt vmcnt(9)
	s_nop 1
	v_mov_b32_e32 v86, v214
	v_mov_b32_e32 v87, v215
	v_mov_b32_e32 v88, v216
	v_mov_b32_e32 v89, v217
	s_nop 1
	v_pk_fma_f32 v[88:89], v[112:113], v[92:93], v[88:89]
	v_pk_fma_f32 v[86:87], v[110:111], v[90:91], v[86:87]
	v_bfe_u32 v104, v86, 16, 1
	v_bfe_u32 v110, v84, 16, 1
	v_bfe_u32 v112, v88, 16, 1
	v_bfe_u32 v105, v87, 16, 1
	v_bfe_u32 v111, v85, 16, 1
	v_bfe_u32 v113, v89, 16, 1
	v_add3_u32 v86, v86, v104, s66
	v_add3_u32 v84, v84, v110, s66
	v_add3_u32 v88, v88, v112, s66
	v_add3_u32 v87, v87, v105, s66
	v_add3_u32 v85, v85, v111, s66
	v_add3_u32 v89, v89, v113, s66
	v_lshrrev_b32_e32 v86, 16, v86
	v_lshrrev_b32_e32 v102, 16, v84
	v_lshrrev_b32_e32 v88, 16, v88
	v_cvt_pk_bf16_f32 v82, v82, v83
	v_and_or_b32 v84, v87, s67, v86
	v_and_or_b32 v83, v85, s67, v102
	v_and_or_b32 v85, v89, s67, v88
	v_permlane16_swap_b32_e32 v82, v84
	s_nop 0
	v_permlane16_swap_b32_e32 v83, v85
	global_store_dwordx4 v[122:123], v[82:85], off offset:256
	s_nop 0
	v_lshlrev_b64 v[102:103], 11, v[114:115]
	v_lshl_add_u64 v[102:103], v[176:177], 0, v[102:103]
	v_lshl_add_u64 v[102:103], v[102:103], 0, v[130:131]
	s_waitcnt vmcnt(8)
	s_nop 1
	v_mov_b32_e32 v82, v218
	v_mov_b32_e32 v83, v219
	v_mov_b32_e32 v84, v220
	v_mov_b32_e32 v85, v221
	s_nop 1
	v_pk_fma_f32 v[68:69], v[68:69], v[108:109], v[84:85]
	v_pk_fma_f32 v[66:67], v[66:67], v[106:107], v[82:83]
	s_waitcnt vmcnt(7)
	s_nop 1
	v_mov_b32_e32 v86, v222
	v_mov_b32_e32 v87, v223
	v_mov_b32_e32 v88, v224
	v_mov_b32_e32 v89, v225
	s_nop 1
	v_pk_fma_f32 v[72:73], v[72:73], v[100:101], v[88:89]
	v_pk_fma_f32 v[70:71], v[70:71], v[98:99], v[86:87]
	v_bfe_u32 v86, v68, 16, 1
	v_bfe_u32 v87, v69, 16, 1
	v_add3_u32 v68, v68, v86, s66
	v_add3_u32 v69, v69, v87, s66
	v_lshrrev_b32_e32 v82, 16, v68
	v_cvt_pk_bf16_f32 v66, v66, v67
	v_cvt_pk_bf16_f32 v68, v70, v71
	v_and_or_b32 v67, v69, s67, v82
	v_cvt_pk_bf16_f32 v69, v72, v73
	v_permlane16_swap_b32_e32 v66, v68
	s_nop 0
	v_permlane16_swap_b32_e32 v67, v69
	global_store_dwordx4 v[102:103], v[66:69], off
	s_nop 0
	s_waitcnt vmcnt(6)
	s_nop 1
	v_mov_b32_e32 v66, v226
	v_mov_b32_e32 v67, v227
	v_mov_b32_e32 v68, v228
	v_mov_b32_e32 v69, v229
	s_nop 1
	v_pk_fma_f32 v[68:69], v[76:77], v[96:97], v[68:69]
	v_pk_fma_f32 v[66:67], v[74:75], v[94:95], v[66:67]
	s_waitcnt vmcnt(5)
	s_nop 1
	v_mov_b32_e32 v70, v230
	v_mov_b32_e32 v71, v231
	v_mov_b32_e32 v72, v232
	v_mov_b32_e32 v73, v233
	s_nop 1
	v_pk_fma_f32 v[72:73], v[80:81], v[92:93], v[72:73]
	v_pk_fma_f32 v[70:71], v[78:79], v[90:91], v[70:71]
	v_cvt_pk_bf16_f32 v130, v66, v67
	v_cvt_pk_bf16_f32 v132, v70, v71
	v_cvt_pk_bf16_f32 v131, v68, v69
	v_cvt_pk_bf16_f32 v133, v72, v73
	v_permlane16_swap_b32_e32 v130, v132
	s_nop 0
	v_permlane16_swap_b32_e32 v131, v133

.LBB0_1397:
	s_or_b64 exec, exec, s[40:41]
	s_and_b32 s37, s63, 1
	s_cmp_lg_u32 s35, s37
	s_cbranch_scc1 .LBB0_1407
	v_mov_b32_e32 v128, 0x3fffff
	buffer_inv sc1
	s_branch .LBB0_1400

.LBB0_1402:
	s_add_i32 s35, s63, 1
	s_cmp_gt_u32 s63, 1
	s_mov_b64 s[40:41], -1
	s_cbranch_scc0 .LBB0_1404
	s_and_b32 s40, s35, 3
	s_lshl_b32 s37, s64, 2
	s_or_b32 s40, s40, s37
	s_mul_i32 s40, s40, 0x18000
	s_add_i32 s40, s40, s31
	s_add_i32 s41, s40, 0x10000
	buffer_load_dwordx4 v[136:139], v189, s[4:7], s41 offen
	s_add_i32 s41, s40, 0x10400
	buffer_load_dwordx4 v[140:143], v189, s[4:7], s41 offen
	s_add_i32 s41, s40, 0x10800
	buffer_load_dwordx4 v[144:147], v189, s[4:7], s41 offen
	s_add_i32 s41, s40, 0x10c00
	buffer_load_dwordx4 v[148:151], v189, s[4:7], s41 offen
	s_add_i32 s41, s40, 0x11000
	buffer_load_dwordx4 v[152:155], v189, s[4:7], s41 offen
	s_add_i32 s41, s40, 0x11400
	buffer_load_dwordx4 v[156:159], v189, s[4:7], s41 offen
	s_add_i32 s41, s40, 0x11800
	s_add_i32 s40, s40, 0x11c00
	buffer_load_dwordx4 v[132:135], v189, s[4:7], s41 offen
	buffer_load_dwordx4 v[128:131], v189, s[4:7], s40 offen
	s_or_b32 s40, s63, s37
	s_xor_b32 s40, s40, 2
	s_mul_i32 s40, s40, 0x18000
	s_add_i32 s40, s40, s31
	s_add_i32 s41, s40, 0x8000
	s_waitcnt vmcnt(7)
	v_cvt_f32_f16_e32 v202, v138
	v_cvt_f32_f16_sdwa v203, v138 dst_sel:DWORD dst_unused:UNUSED_PAD src0_sel:WORD_1
	v_cvt_f32_f16_e32 v138, v139
	v_cvt_f32_f16_sdwa v139, v139 dst_sel:DWORD dst_unused:UNUSED_PAD src0_sel:WORD_1
	s_waitcnt vmcnt(6)
	v_cvt_f32_f16_e32 v204, v140
	v_cvt_f32_f16_sdwa v205, v140 dst_sel:DWORD dst_unused:UNUSED_PAD src0_sel:WORD_1
	v_cvt_f32_f16_e32 v140, v141
	v_cvt_f32_f16_sdwa v141, v141 dst_sel:DWORD dst_unused:UNUSED_PAD src0_sel:WORD_1
	v_cvt_f32_f16_e32 v206, v142
	v_cvt_f32_f16_sdwa v207, v142 dst_sel:DWORD dst_unused:UNUSED_PAD src0_sel:WORD_1
	v_cvt_f32_f16_e32 v142, v143
	v_cvt_f32_f16_sdwa v143, v143 dst_sel:DWORD dst_unused:UNUSED_PAD src0_sel:WORD_1
	s_waitcnt vmcnt(5)
	v_cvt_f32_f16_e32 v210, v146
	v_cvt_f32_f16_sdwa v211, v146 dst_sel:DWORD dst_unused:UNUSED_PAD src0_sel:WORD_1
	v_cvt_f32_f16_e32 v212, v147
	v_cvt_f32_f16_sdwa v213, v147 dst_sel:DWORD dst_unused:UNUSED_PAD src0_sel:WORD_1
	s_waitcnt vmcnt(4)
	v_cvt_f32_f16_e32 v214, v148
	v_cvt_f32_f16_sdwa v215, v148 dst_sel:DWORD dst_unused:UNUSED_PAD src0_sel:WORD_1
	v_cvt_f32_f16_e32 v148, v149
	v_cvt_f32_f16_sdwa v149, v149 dst_sel:DWORD dst_unused:UNUSED_PAD src0_sel:WORD_1
	v_cvt_f32_f16_e32 v216, v150
	v_cvt_f32_f16_sdwa v217, v150 dst_sel:DWORD dst_unused:UNUSED_PAD src0_sel:WORD_1
	v_cvt_f32_f16_e32 v150, v151
	v_cvt_f32_f16_sdwa v151, v151 dst_sel:DWORD dst_unused:UNUSED_PAD src0_sel:WORD_1
	s_waitcnt vmcnt(3)
	v_cvt_f32_f16_e32 v218, v152
	v_cvt_f32_f16_sdwa v219, v152 dst_sel:DWORD dst_unused:UNUSED_PAD src0_sel:WORD_1
	v_cvt_f32_f16_e32 v152, v153
	v_cvt_f32_f16_sdwa v153, v153 dst_sel:DWORD dst_unused:UNUSED_PAD src0_sel:WORD_1
	v_cvt_f32_f16_e32 v220, v154
	v_cvt_f32_f16_sdwa v221, v154 dst_sel:DWORD dst_unused:UNUSED_PAD src0_sel:WORD_1
	v_cvt_f32_f16_e32 v154, v155
	v_cvt_f32_f16_sdwa v155, v155 dst_sel:DWORD dst_unused:UNUSED_PAD src0_sel:WORD_1
	v_cvt_f32_f16_e32 v200, v136
	v_cvt_f32_f16_sdwa v201, v136 dst_sel:DWORD dst_unused:UNUSED_PAD src0_sel:WORD_1
	v_cvt_f32_f16_e32 v136, v137
	v_cvt_f32_f16_sdwa v137, v137 dst_sel:DWORD dst_unused:UNUSED_PAD src0_sel:WORD_1
	v_cvt_f32_f16_e32 v208, v144
	v_cvt_f32_f16_sdwa v209, v144 dst_sel:DWORD dst_unused:UNUSED_PAD src0_sel:WORD_1
	v_cvt_f32_f16_e32 v144, v145
	v_cvt_f32_f16_sdwa v145, v145 dst_sel:DWORD dst_unused:UNUSED_PAD src0_sel:WORD_1
	s_waitcnt vmcnt(2)
	v_cvt_f32_f16_e32 v222, v156
	v_cvt_f32_f16_sdwa v223, v156 dst_sel:DWORD dst_unused:UNUSED_PAD src0_sel:WORD_1
	v_cvt_f32_f16_e32 v224, v157
	v_cvt_f32_f16_sdwa v225, v157 dst_sel:DWORD dst_unused:UNUSED_PAD src0_sel:WORD_1
	v_cvt_f32_f16_e32 v226, v158
	v_cvt_f32_f16_sdwa v227, v158 dst_sel:DWORD dst_unused:UNUSED_PAD src0_sel:WORD_1
	v_cvt_f32_f16_e32 v228, v159
	v_cvt_f32_f16_sdwa v229, v159 dst_sel:DWORD dst_unused:UNUSED_PAD src0_sel:WORD_1
	v_pk_add_f32 v[122:123], v[122:123], v[138:139]
	v_pk_add_f32 v[138:139], v[118:119], v[140:141]
	v_pk_add_f32 v[142:143], v[114:115], v[142:143]
	v_pk_add_f32 v[140:141], v[112:113], v[206:207]
	v_pk_add_f32 v[158:159], v[106:107], v[212:213]
	v_pk_add_f32 v[156:157], v[104:105], v[210:211]
	v_pk_add_f32 v[114:115], v[102:103], v[148:149]
	v_pk_add_f32 v[112:113], v[100:101], v[214:215]
	v_pk_add_f32 v[106:107], v[98:99], v[150:151]
	v_pk_add_f32 v[104:105], v[96:97], v[216:217]
	v_pk_add_f32 v[102:103], v[94:95], v[152:153]
	v_pk_add_f32 v[100:101], v[92:93], v[218:219]
	v_pk_add_f32 v[98:99], v[90:91], v[154:155]
	v_pk_add_f32 v[96:97], v[88:89], v[220:221]
	s_waitcnt vmcnt(1)
	v_cvt_f32_f16_e32 v88, v132
	v_cvt_f32_f16_sdwa v89, v132 dst_sel:DWORD dst_unused:UNUSED_PAD src0_sel:WORD_1
	v_cvt_f32_f16_e32 v90, v133
	v_cvt_f32_f16_sdwa v91, v133 dst_sel:DWORD dst_unused:UNUSED_PAD src0_sel:WORD_1
	v_cvt_f32_f16_e32 v92, v134
	v_cvt_f32_f16_e32 v94, v135
	v_cvt_f32_f16_sdwa v95, v135 dst_sel:DWORD dst_unused:UNUSED_PAD src0_sel:WORD_1
	v_cvt_f32_f16_sdwa v93, v134 dst_sel:DWORD dst_unused:UNUSED_PAD src0_sel:WORD_1
	v_pk_add_f32 v[126:127], v[126:127], v[136:137]
	v_pk_add_f32 v[124:125], v[124:125], v[200:201]
	v_pk_add_f32 v[120:121], v[120:121], v[202:203]
	v_pk_add_f32 v[136:137], v[116:117], v[204:205]
	v_pk_add_f32 v[146:147], v[110:111], v[144:145]
	v_pk_add_f32 v[144:145], v[108:109], v[208:209]
	v_pk_add_f32 v[78:79], v[78:79], v[90:91]
	v_pk_add_f32 v[76:77], v[76:77], v[88:89]
	v_pk_add_f32 v[74:75], v[74:75], v[94:95]
	v_pk_add_f32 v[72:73], v[72:73], v[92:93]
	s_waitcnt vmcnt(0)
	v_cvt_f32_f16_e32 v88, v128
	v_cvt_f32_f16_sdwa v89, v128 dst_sel:DWORD dst_unused:UNUSED_PAD src0_sel:WORD_1
	v_cvt_f32_f16_e32 v90, v129
	v_cvt_f32_f16_sdwa v91, v129 dst_sel:DWORD dst_unused:UNUSED_PAD src0_sel:WORD_1
	v_cvt_f32_f16_e32 v92, v130
	v_cvt_f32_f16_e32 v94, v131
	v_cvt_f32_f16_sdwa v95, v131 dst_sel:DWORD dst_unused:UNUSED_PAD src0_sel:WORD_1
	v_cvt_f32_f16_sdwa v93, v130 dst_sel:DWORD dst_unused:UNUSED_PAD src0_sel:WORD_1
	v_pk_add_f32 v[86:87], v[86:87], v[224:225]
	v_pk_add_f32 v[84:85], v[84:85], v[222:223]
	v_pk_add_f32 v[82:83], v[82:83], v[228:229]
	v_pk_add_f32 v[80:81], v[80:81], v[226:227]
	v_pk_add_f32 v[70:71], v[70:71], v[90:91]
	v_pk_add_f32 v[68:69], v[68:69], v[88:89]
	v_pk_add_f32 v[66:67], v[66:67], v[94:95]
	v_pk_add_f32 v[64:65], v[64:65], v[92:93]
	s_nop 0
	buffer_load_dwordx4 v[88:91], v189, s[4:7], s41 offen
	s_add_i32 s41, s40, 0x8400
	buffer_load_dwordx4 v[92:95], v189, s[4:7], s41 offen
	s_add_i32 s41, s40, 0x8800
	buffer_load_dwordx4 v[128:131], v189, s[4:7], s41 offen
	s_add_i32 s41, s40, 0x8c00
	buffer_load_dwordx4 v[200:203], v189, s[4:7], s41 offen
	s_add_i32 s41, s40, 0x9000
	buffer_load_dwordx4 v[204:207], v189, s[4:7], s41 offen
	s_add_i32 s41, s40, 0x9400
	buffer_load_dwordx4 v[208:211], v189, s[4:7], s41 offen
	s_add_i32 s41, s40, 0x9800
	s_add_i32 s40, s40, 0x9c00
	buffer_load_dwordx4 v[116:119], v189, s[4:7], s41 offen
	buffer_load_dwordx4 v[108:111], v189, s[4:7], s40 offen
	s_add_i32 s40, s63, -1
	s_and_b32 s40, s40, 3
	s_or_b32 s37, s40, s37
	s_mul_i32 s37, s37, 0x18000
	s_add_i32 s37, s31, s37
	s_or_b32 s40, s37, 0x400
	s_waitcnt vmcnt(7)
	v_cvt_f32_f16_e32 v132, v88
	v_cvt_f32_f16_sdwa v133, v88 dst_sel:DWORD dst_unused:UNUSED_PAD src0_sel:WORD_1
	v_cvt_f32_f16_e32 v88, v89
	v_cvt_f32_f16_sdwa v89, v89 dst_sel:DWORD dst_unused:UNUSED_PAD src0_sel:WORD_1
	s_waitcnt vmcnt(6)
	v_cvt_f32_f16_e32 v150, v92
	v_cvt_f32_f16_sdwa v151, v92 dst_sel:DWORD dst_unused:UNUSED_PAD src0_sel:WORD_1
	v_cvt_f32_f16_e32 v92, v93
	v_cvt_f32_f16_sdwa v93, v93 dst_sel:DWORD dst_unused:UNUSED_PAD src0_sel:WORD_1
	v_cvt_f32_f16_e32 v212, v94
	v_cvt_f32_f16_sdwa v213, v94 dst_sel:DWORD dst_unused:UNUSED_PAD src0_sel:WORD_1
	v_cvt_f32_f16_e32 v94, v95
	v_cvt_f32_f16_sdwa v95, v95 dst_sel:DWORD dst_unused:UNUSED_PAD src0_sel:WORD_1
	v_cvt_f32_f16_e32 v148, v90
	v_cvt_f32_f16_sdwa v149, v90 dst_sel:DWORD dst_unused:UNUSED_PAD src0_sel:WORD_1
	v_cvt_f32_f16_e32 v90, v91
	v_cvt_f32_f16_sdwa v91, v91 dst_sel:DWORD dst_unused:UNUSED_PAD src0_sel:WORD_1
	s_waitcnt vmcnt(4)
	v_cvt_f32_f16_e32 v220, v200
	v_cvt_f32_f16_sdwa v221, v200 dst_sel:DWORD dst_unused:UNUSED_PAD src0_sel:WORD_1
	v_pk_add_f32 v[134:135], v[126:127], v[88:89]
	v_pk_add_f32 v[154:155], v[138:139], v[92:93]
	v_pk_add_f32 v[152:153], v[136:137], v[150:151]
	v_pk_add_f32 v[150:151], v[142:143], v[94:95]
	v_cvt_f32_f16_e32 v88, v201
	v_cvt_f32_f16_sdwa v89, v201 dst_sel:DWORD dst_unused:UNUSED_PAD src0_sel:WORD_1
	v_cvt_f32_f16_e32 v92, v202
	v_cvt_f32_f16_e32 v94, v203
	v_cvt_f32_f16_sdwa v95, v203 dst_sel:DWORD dst_unused:UNUSED_PAD src0_sel:WORD_1
	v_cvt_f32_f16_sdwa v93, v202 dst_sel:DWORD dst_unused:UNUSED_PAD src0_sel:WORD_1
	v_pk_add_f32 v[126:127], v[122:123], v[90:91]
	v_pk_add_f32 v[90:91], v[114:115], v[88:89]
	v_pk_add_f32 v[88:89], v[112:113], v[220:221]
	v_pk_add_f32 v[94:95], v[106:107], v[94:95]
	v_pk_add_f32 v[92:93], v[104:105], v[92:93]
	s_waitcnt vmcnt(3)
	v_cvt_f32_f16_e32 v104, v204
	v_cvt_f32_f16_sdwa v105, v204 dst_sel:DWORD dst_unused:UNUSED_PAD src0_sel:WORD_1
	v_cvt_f32_f16_e32 v106, v205
	v_cvt_f32_f16_sdwa v107, v205 dst_sel:DWORD dst_unused:UNUSED_PAD src0_sel:WORD_1
	v_cvt_f32_f16_e32 v112, v206
	v_cvt_f32_f16_e32 v114, v207
	v_cvt_f32_f16_sdwa v115, v207 dst_sel:DWORD dst_unused:UNUSED_PAD src0_sel:WORD_1
	v_cvt_f32_f16_sdwa v113, v206 dst_sel:DWORD dst_unused:UNUSED_PAD src0_sel:WORD_1
	v_pk_add_f32 v[102:103], v[102:103], v[106:107]
	v_pk_add_f32 v[100:101], v[100:101], v[104:105]
	v_pk_add_f32 v[106:107], v[98:99], v[114:115]
	v_pk_add_f32 v[104:105], v[96:97], v[112:113]
	s_waitcnt vmcnt(2)
	v_cvt_f32_f16_e32 v96, v208
	v_cvt_f32_f16_sdwa v97, v208 dst_sel:DWORD dst_unused:UNUSED_PAD src0_sel:WORD_1
	v_cvt_f32_f16_e32 v98, v209
	v_cvt_f32_f16_sdwa v99, v209 dst_sel:DWORD dst_unused:UNUSED_PAD src0_sel:WORD_1
	v_cvt_f32_f16_e32 v214, v128
	v_cvt_f32_f16_sdwa v215, v128 dst_sel:DWORD dst_unused:UNUSED_PAD src0_sel:WORD_1
	v_cvt_f32_f16_e32 v128, v129
	v_cvt_f32_f16_sdwa v129, v129 dst_sel:DWORD dst_unused:UNUSED_PAD src0_sel:WORD_1
	v_cvt_f32_f16_e32 v216, v130
	v_cvt_f32_f16_sdwa v217, v130 dst_sel:DWORD dst_unused:UNUSED_PAD src0_sel:WORD_1
	v_cvt_f32_f16_e32 v218, v131
	v_cvt_f32_f16_sdwa v219, v131 dst_sel:DWORD dst_unused:UNUSED_PAD src0_sel:WORD_1
	v_cvt_f32_f16_e32 v112, v210
	v_cvt_f32_f16_e32 v114, v211
	v_cvt_f32_f16_sdwa v115, v211 dst_sel:DWORD dst_unused:UNUSED_PAD src0_sel:WORD_1
	v_cvt_f32_f16_sdwa v113, v210 dst_sel:DWORD dst_unused:UNUSED_PAD src0_sel:WORD_1
	v_pk_add_f32 v[86:87], v[86:87], v[98:99]
	v_pk_add_f32 v[84:85], v[84:85], v[96:97]
	s_waitcnt vmcnt(1)
	v_cvt_f32_f16_e32 v96, v116
	v_cvt_f32_f16_sdwa v97, v116 dst_sel:DWORD dst_unused:UNUSED_PAD src0_sel:WORD_1
	v_cvt_f32_f16_e32 v98, v117
	v_cvt_f32_f16_sdwa v99, v117 dst_sel:DWORD dst_unused:UNUSED_PAD src0_sel:WORD_1
	v_cvt_f32_f16_e32 v116, v118
	v_cvt_f32_f16_e32 v136, v119
	v_cvt_f32_f16_sdwa v137, v119 dst_sel:DWORD dst_unused:UNUSED_PAD src0_sel:WORD_1
	v_cvt_f32_f16_sdwa v117, v118 dst_sel:DWORD dst_unused:UNUSED_PAD src0_sel:WORD_1
	v_pk_add_f32 v[132:133], v[124:125], v[132:133]
	v_pk_add_f32 v[124:125], v[120:121], v[148:149]
	v_pk_add_f32 v[148:149], v[140:141], v[212:213]
	v_pk_add_f32 v[130:131], v[146:147], v[128:129]
	v_pk_add_f32 v[128:129], v[144:145], v[214:215]
	v_pk_add_f32 v[122:123], v[158:159], v[218:219]
	v_pk_add_f32 v[120:121], v[156:157], v[216:217]
	v_pk_add_f32 v[82:83], v[82:83], v[114:115]
	v_pk_add_f32 v[80:81], v[80:81], v[112:113]
	v_pk_add_f32 v[114:115], v[78:79], v[98:99]
	v_pk_add_f32 v[112:113], v[76:77], v[96:97]
	v_pk_add_f32 v[118:119], v[74:75], v[136:137]
	v_pk_add_f32 v[116:117], v[72:73], v[116:117]
	s_waitcnt vmcnt(0)
	v_cvt_f32_f16_e32 v72, v108
	v_cvt_f32_f16_sdwa v73, v108 dst_sel:DWORD dst_unused:UNUSED_PAD src0_sel:WORD_1
	v_cvt_f32_f16_e32 v74, v109
	v_cvt_f32_f16_sdwa v75, v109 dst_sel:DWORD dst_unused:UNUSED_PAD src0_sel:WORD_1
	v_cvt_f32_f16_e32 v76, v110
	v_cvt_f32_f16_e32 v78, v111
	v_cvt_f32_f16_sdwa v79, v111 dst_sel:DWORD dst_unused:UNUSED_PAD src0_sel:WORD_1
	v_cvt_f32_f16_sdwa v77, v110 dst_sel:DWORD dst_unused:UNUSED_PAD src0_sel:WORD_1
	v_pk_add_f32 v[138:139], v[70:71], v[74:75]
	v_pk_add_f32 v[136:137], v[68:69], v[72:73]
	v_pk_add_f32 v[142:143], v[66:67], v[78:79]
	v_pk_add_f32 v[140:141], v[64:65], v[76:77]
	s_nop 0
	buffer_load_dwordx4 v[64:67], v189, s[4:7], s37 offen
	buffer_load_dwordx4 v[68:71], v189, s[4:7], s40 offen
	s_or_b32 s40, s37, 0x800
	buffer_load_dwordx4 v[72:75], v189, s[4:7], s40 offen
	s_or_b32 s40, s37, 0xc00
	buffer_load_dwordx4 v[200:203], v189, s[4:7], s40 offen
	s_or_b32 s40, s37, 0x1000
	buffer_load_dwordx4 v[204:207], v189, s[4:7], s40 offen
	s_or_b32 s40, s37, 0x1400
	buffer_load_dwordx4 v[208:211], v189, s[4:7], s40 offen
	s_or_b32 s40, s37, 0x1800
	s_or_b32 s37, s37, 0x1c00
	buffer_load_dwordx4 v[156:159], v189, s[4:7], s40 offen
	buffer_load_dwordx4 v[144:147], v189, s[4:7], s37 offen
	s_mov_b64 s[40:41], 0
	s_waitcnt vmcnt(7)
	v_cvt_f32_f16_e32 v76, v64
	v_cvt_f32_f16_sdwa v77, v64 dst_sel:DWORD dst_unused:UNUSED_PAD src0_sel:WORD_1
	v_cvt_f32_f16_e32 v64, v65
	v_cvt_f32_f16_sdwa v65, v65 dst_sel:DWORD dst_unused:UNUSED_PAD src0_sel:WORD_1
	v_cvt_f32_f16_e32 v78, v66
	v_cvt_f32_f16_e32 v96, v67
	v_cvt_f32_f16_sdwa v97, v67 dst_sel:DWORD dst_unused:UNUSED_PAD src0_sel:WORD_1
	v_cvt_f32_f16_sdwa v79, v66 dst_sel:DWORD dst_unused:UNUSED_PAD src0_sel:WORD_1
	v_pk_add_f32 v[134:135], v[134:135], v[64:65]
	s_waitcnt vmcnt(6)
	v_cvt_f32_f16_e32 v64, v68
	v_cvt_f32_f16_sdwa v65, v68 dst_sel:DWORD dst_unused:UNUSED_PAD src0_sel:WORD_1
	v_cvt_f32_f16_e32 v66, v69
	v_cvt_f32_f16_sdwa v67, v69 dst_sel:DWORD dst_unused:UNUSED_PAD src0_sel:WORD_1
	v_cvt_f32_f16_e32 v68, v70
	v_cvt_f32_f16_sdwa v69, v70 dst_sel:DWORD dst_unused:UNUSED_PAD src0_sel:WORD_1
	v_pk_add_f32 v[132:133], v[132:133], v[76:77]
	v_pk_add_f32 v[126:127], v[126:127], v[96:97]
	v_cvt_f32_f16_e32 v76, v71
	v_cvt_f32_f16_sdwa v77, v71 dst_sel:DWORD dst_unused:UNUSED_PAD src0_sel:WORD_1
	v_pk_add_f32 v[108:109], v[152:153], v[64:65]
	v_pk_add_f32 v[96:97], v[148:149], v[68:69]
	s_waitcnt vmcnt(5)
	v_cvt_f32_f16_e32 v64, v72
	v_cvt_f32_f16_sdwa v65, v72 dst_sel:DWORD dst_unused:UNUSED_PAD src0_sel:WORD_1
	v_cvt_f32_f16_e32 v68, v74
	v_cvt_f32_f16_sdwa v69, v74 dst_sel:DWORD dst_unused:UNUSED_PAD src0_sel:WORD_1
	v_pk_add_f32 v[110:111], v[154:155], v[66:67]
	v_cvt_f32_f16_e32 v66, v73
	v_cvt_f32_f16_sdwa v67, v73 dst_sel:DWORD dst_unused:UNUSED_PAD src0_sel:WORD_1
	v_cvt_f32_f16_e32 v70, v75
	v_cvt_f32_f16_sdwa v71, v75 dst_sel:DWORD dst_unused:UNUSED_PAD src0_sel:WORD_1
	v_pk_add_f32 v[98:99], v[150:151], v[76:77]
	v_pk_add_f32 v[76:77], v[128:129], v[64:65]
	v_pk_add_f32 v[72:73], v[120:121], v[68:69]
	s_waitcnt vmcnt(4)
	v_cvt_f32_f16_e32 v64, v200
	v_cvt_f32_f16_sdwa v65, v200 dst_sel:DWORD dst_unused:UNUSED_PAD src0_sel:WORD_1
	v_cvt_f32_f16_e32 v120, v202
	v_cvt_f32_f16_sdwa v121, v202 dst_sel:DWORD dst_unused:UNUSED_PAD src0_sel:WORD_1
	v_pk_add_f32 v[124:125], v[124:125], v[78:79]
	v_pk_add_f32 v[78:79], v[130:131], v[66:67]
	v_pk_add_f32 v[74:75], v[122:123], v[70:71]
	v_cvt_f32_f16_e32 v66, v201
	v_cvt_f32_f16_sdwa v67, v201 dst_sel:DWORD dst_unused:UNUSED_PAD src0_sel:WORD_1
	v_cvt_f32_f16_e32 v122, v203
	v_cvt_f32_f16_sdwa v123, v203 dst_sel:DWORD dst_unused:UNUSED_PAD src0_sel:WORD_1
	v_pk_add_f32 v[68:69], v[88:89], v[64:65]
	v_pk_add_f32 v[64:65], v[92:93], v[120:121]
	s_waitcnt vmcnt(3)
	v_cvt_f32_f16_e32 v92, v206
	v_cvt_f32_f16_sdwa v93, v206 dst_sel:DWORD dst_unused:UNUSED_PAD src0_sel:WORD_1
	v_pk_add_f32 v[70:71], v[90:91], v[66:67]
	v_pk_add_f32 v[66:67], v[94:95], v[122:123]
	v_cvt_f32_f16_e32 v94, v207
	v_cvt_f32_f16_sdwa v95, v207 dst_sel:DWORD dst_unused:UNUSED_PAD src0_sel:WORD_1
	v_cvt_f32_f16_e32 v88, v204
	v_cvt_f32_f16_sdwa v89, v204 dst_sel:DWORD dst_unused:UNUSED_PAD src0_sel:WORD_1
	v_pk_add_f32 v[152:153], v[104:105], v[92:93]
	s_waitcnt vmcnt(2)
	v_cvt_f32_f16_e32 v92, v210
	v_cvt_f32_f16_sdwa v93, v210 dst_sel:DWORD dst_unused:UNUSED_PAD src0_sel:WORD_1
	v_cvt_f32_f16_e32 v90, v205
	v_cvt_f32_f16_sdwa v91, v205 dst_sel:DWORD dst_unused:UNUSED_PAD src0_sel:WORD_1
	v_pk_add_f32 v[154:155], v[106:107], v[94:95]
	v_cvt_f32_f16_e32 v94, v211
	v_cvt_f32_f16_sdwa v95, v211 dst_sel:DWORD dst_unused:UNUSED_PAD src0_sel:WORD_1
	v_pk_add_f32 v[148:149], v[100:101], v[88:89]
	v_cvt_f32_f16_e32 v88, v208
	v_cvt_f32_f16_sdwa v89, v208 dst_sel:DWORD dst_unused:UNUSED_PAD src0_sel:WORD_1
	v_pk_add_f32 v[128:129], v[80:81], v[92:93]
	s_waitcnt vmcnt(1)
	v_cvt_f32_f16_e32 v80, v156
	v_cvt_f32_f16_sdwa v81, v156 dst_sel:DWORD dst_unused:UNUSED_PAD src0_sel:WORD_1
	v_pk_add_f32 v[150:151], v[102:103], v[90:91]
	v_cvt_f32_f16_e32 v90, v209
	v_cvt_f32_f16_sdwa v91, v209 dst_sel:DWORD dst_unused:UNUSED_PAD src0_sel:WORD_1
	v_pk_add_f32 v[130:131], v[82:83], v[94:95]
	v_cvt_f32_f16_e32 v82, v157
	v_cvt_f32_f16_sdwa v83, v157 dst_sel:DWORD dst_unused:UNUSED_PAD src0_sel:WORD_1
	v_pk_add_f32 v[120:121], v[84:85], v[88:89]
	v_cvt_f32_f16_e32 v84, v158
	v_cvt_f32_f16_sdwa v85, v158 dst_sel:DWORD dst_unused:UNUSED_PAD src0_sel:WORD_1
	v_pk_add_f32 v[100:101], v[112:113], v[80:81]
	s_waitcnt vmcnt(0)
	v_cvt_f32_f16_e32 v80, v144
	v_cvt_f32_f16_sdwa v81, v144 dst_sel:DWORD dst_unused:UNUSED_PAD src0_sel:WORD_1
	v_cvt_f32_f16_e32 v88, v146
	v_cvt_f32_f16_sdwa v89, v146 dst_sel:DWORD dst_unused:UNUSED_PAD src0_sel:WORD_1
	v_pk_add_f32 v[122:123], v[86:87], v[90:91]
	v_cvt_f32_f16_e32 v86, v159
	v_cvt_f32_f16_sdwa v87, v159 dst_sel:DWORD dst_unused:UNUSED_PAD src0_sel:WORD_1
	v_pk_add_f32 v[102:103], v[114:115], v[82:83]
	v_cvt_f32_f16_e32 v82, v145
	v_cvt_f32_f16_sdwa v83, v145 dst_sel:DWORD dst_unused:UNUSED_PAD src0_sel:WORD_1
	v_cvt_f32_f16_e32 v90, v147
	v_cvt_f32_f16_sdwa v91, v147 dst_sel:DWORD dst_unused:UNUSED_PAD src0_sel:WORD_1
	v_pk_add_f32 v[104:105], v[116:117], v[84:85]
	v_pk_add_f32 v[84:85], v[136:137], v[80:81]
	v_pk_add_f32 v[80:81], v[140:141], v[88:89]
	v_and_b32_e32 v88, 1, v197
	v_add_u32_e32 v89, 12, v199
	v_cmp_eq_u32_e32 vcc, 0, v88
	v_pk_add_f32 v[106:107], v[118:119], v[86:87]
	v_pk_add_f32 v[86:87], v[138:139], v[82:83]
	v_pk_add_f32 v[82:83], v[142:143], v[90:91]
	v_cndmask_b32_e32 v88, v89, v199, vcc
	v_add_u32_e32 v142, 0x80, v188
	v_add_u32_e32 v88, v88, v198
	v_ashrrev_i32_e32 v143, 31, v142
	v_ashrrev_i32_e32 v89, 31, v88
	v_lshlrev_b64 v[90:91], 11, v[142:143]
	v_lshl_add_u64 v[90:91], v[170:171], 0, v[90:91]
	v_lshlrev_b64 v[136:137], 1, v[88:89]
	v_lshl_add_u64 v[144:145], v[90:91], 0, v[136:137]
	global_load_dwordx4 v[116:119], v[190:191], off
	global_load_dwordx4 v[112:115], v[190:191], off offset:64
	global_load_dwordx4 v[92:95], v[190:191], off offset:512
	global_load_dwordx4 v[88:91], v[190:191], off offset:576
	s_mov_b64 s[78:79], 0x8000
	v_mov_b32_e32 v250, v144
	v_mov_b32_e32 v251, v145
	global_load_dwordx4 v[200:203], v[250:251], off
	global_load_dwordx4 v[204:207], v[250:251], off offset:256
	v_lshl_add_u64 v[250:251], v[250:251], 0, s[78:79]
	global_load_dwordx4 v[208:211], v[250:251], off
	global_load_dwordx4 v[212:215], v[250:251], off offset:256
	v_lshl_add_u64 v[250:251], v[250:251], 0, s[78:79]
	global_load_dwordx4 v[216:219], v[250:251], off
	s_waitcnt vmcnt(4)
	s_nop 1
	v_mov_b32_e32 v138, v200
	v_mov_b32_e32 v139, v201
	v_mov_b32_e32 v140, v202
	v_mov_b32_e32 v141, v203
	global_load_dwordx4 v[200:203], v[250:251], off offset:256
	s_nop 1
	v_permlane16_swap_b32_e32 v138, v140
	v_permlane16_swap_b32_e32 v139, v141
	v_lshlrev_b32_e32 v146, 16, v138
	v_and_b32_e32 v147, 0xffff0000, v138
	v_lshlrev_b32_e32 v138, 16, v139
	v_and_b32_e32 v139, 0xffff0000, v139
	v_lshlrev_b32_e32 v156, 16, v140
	v_and_b32_e32 v157, 0xffff0000, v140
	v_lshlrev_b32_e32 v158, 16, v141
	v_and_b32_e32 v159, 0xffff0000, v141
	v_pk_fma_f32 v[140:141], v[134:135], v[118:119], v[138:139]
	v_pk_fma_f32 v[138:139], v[132:133], v[116:117], v[146:147]
	v_lshlrev_b64 v[132:133], 12, v[142:143]
	v_lshl_add_u64 v[134:135], s[0:1], 0, v[132:133]
	v_lshlrev_b64 v[132:133], 2, v[186:187]
	v_lshl_add_u64 v[134:135], v[134:135], 0, v[132:133]
	v_pk_fma_f32 v[126:127], v[126:127], v[114:115], v[158:159]
	v_pk_fma_f32 v[124:125], v[124:125], v[112:113], v[156:157]
	global_store_dwordx4 v[134:135], v[138:141], off
	global_store_dwordx4 v[134:135], v[124:127], off offset:64
	v_add_u32_e32 v142, 0x90, v188
	v_ashrrev_i32_e32 v143, 31, v142
	v_lshlrev_b64 v[138:139], 11, v[142:143]
	v_lshl_add_u64 v[138:139], v[170:171], 0, v[138:139]
	v_lshl_add_u64 v[144:145], v[138:139], 0, v[136:137]
	s_waitcnt vmcnt(6)
	s_nop 1
	v_mov_b32_e32 v124, v204
	v_mov_b32_e32 v125, v205
	v_mov_b32_e32 v126, v206
	v_mov_b32_e32 v127, v207
	v_lshl_add_u64 v[250:251], v[250:251], 0, s[78:79]
	global_load_dwordx4 v[204:207], v[250:251], off
	s_nop 1
	v_permlane16_swap_b32_e32 v124, v126
	v_permlane16_swap_b32_e32 v125, v127
	v_lshlrev_b32_e32 v138, 16, v124
	v_and_b32_e32 v139, 0xffff0000, v124
	v_lshlrev_b32_e32 v124, 16, v125
	v_and_b32_e32 v125, 0xffff0000, v125
	v_lshlrev_b32_e32 v146, 16, v126
	v_and_b32_e32 v147, 0xffff0000, v126
	v_lshlrev_b32_e32 v140, 16, v127
	v_and_b32_e32 v141, 0xffff0000, v127
	v_pk_fma_f32 v[126:127], v[150:151], v[94:95], v[124:125]
	v_pk_fma_f32 v[124:125], v[148:149], v[92:93], v[138:139]
	v_pk_fma_f32 v[140:141], v[154:155], v[90:91], v[140:141]
	v_pk_fma_f32 v[138:139], v[152:153], v[88:89], v[146:147]
	global_store_dwordx4 v[134:135], v[124:127], off offset:512
	global_store_dwordx4 v[134:135], v[138:141], off offset:576
	v_lshlrev_b64 v[134:135], 12, v[142:143]
	v_lshl_add_u64 v[134:135], s[0:1], 0, v[134:135]
	v_lshl_add_u64 v[134:135], v[134:135], 0, v[132:133]
	s_waitcnt vmcnt(8)
	s_nop 1
	v_mov_b32_e32 v124, v208
	v_mov_b32_e32 v125, v209
	v_mov_b32_e32 v126, v210
	v_mov_b32_e32 v127, v211
	global_load_dwordx4 v[208:211], v[250:251], off offset:256
	s_nop 1
	v_mov_b32_e32 v139, v126
	v_mov_b32_e32 v141, v127
	s_nop 0
	v_permlane16_swap_b32_e32 v124, v139
	v_permlane16_swap_b32_e32 v125, v141
	v_lshlrev_b32_e32 v126, 16, v124
	v_and_b32_e32 v127, 0xffff0000, v124
	v_lshlrev_b32_e32 v124, 16, v125
	v_and_b32_e32 v125, 0xffff0000, v125
	v_lshlrev_b32_e32 v138, 16, v139
	v_and_b32_e32 v139, 0xffff0000, v139
	v_lshlrev_b32_e32 v140, 16, v141
	v_and_b32_e32 v141, 0xffff0000, v141
	v_pk_fma_f32 v[110:111], v[110:111], v[118:119], v[124:125]
	v_pk_fma_f32 v[108:109], v[108:109], v[116:117], v[126:127]
	v_pk_fma_f32 v[98:99], v[98:99], v[114:115], v[140:141]
	v_pk_fma_f32 v[96:97], v[96:97], v[112:113], v[138:139]
	global_store_dwordx4 v[134:135], v[108:111], off
	global_store_dwordx4 v[134:135], v[96:99], off offset:64
	v_add_u32_e32 v124, 0xa0, v188
	v_ashrrev_i32_e32 v125, 31, v124
	v_lshlrev_b64 v[108:109], 11, v[124:125]
	v_lshl_add_u64 v[108:109], v[170:171], 0, v[108:109]
	v_lshl_add_u64 v[126:127], v[108:109], 0, v[136:137]
	s_waitcnt vmcnt(10)
	s_nop 1
	v_mov_b32_e32 v96, v212
	v_mov_b32_e32 v97, v213
	v_mov_b32_e32 v98, v214
	v_mov_b32_e32 v99, v215
	s_nop 1
	v_permlane16_swap_b32_e32 v96, v98
	v_permlane16_swap_b32_e32 v97, v99
	v_lshlrev_b32_e32 v108, 16, v96
	v_and_b32_e32 v109, 0xffff0000, v96
	v_lshlrev_b32_e32 v96, 16, v97
	v_and_b32_e32 v97, 0xffff0000, v97
	v_lshlrev_b32_e32 v138, 16, v98
	v_and_b32_e32 v139, 0xffff0000, v98
	v_lshlrev_b32_e32 v110, 16, v99
	v_and_b32_e32 v111, 0xffff0000, v99
	v_pk_fma_f32 v[98:99], v[122:123], v[94:95], v[96:97]
	v_pk_fma_f32 v[96:97], v[120:121], v[92:93], v[108:109]
	v_pk_fma_f32 v[110:111], v[130:131], v[90:91], v[110:111]
	v_pk_fma_f32 v[108:109], v[128:129], v[88:89], v[138:139]
	global_store_dwordx4 v[134:135], v[96:99], off offset:512
	global_store_dwordx4 v[134:135], v[108:111], off offset:576
	s_waitcnt vmcnt(11)
	s_nop 1
	v_mov_b32_e32 v96, v216
	v_mov_b32_e32 v97, v217
	v_mov_b32_e32 v98, v218
	v_mov_b32_e32 v99, v219
	s_nop 1
	v_mov_b32_e32 v121, v99
	v_mov_b32_e32 v111, v98
	v_lshlrev_b64 v[108:109], 12, v[124:125]
	s_nop 0
	v_permlane16_swap_b32_e32 v96, v111
	v_permlane16_swap_b32_e32 v97, v121
	v_lshl_add_u64 v[108:109], s[0:1], 0, v[108:109]
	v_lshlrev_b32_e32 v98, 16, v96
	v_and_b32_e32 v99, 0xffff0000, v96
	v_lshlrev_b32_e32 v96, 16, v97
	v_and_b32_e32 v97, 0xffff0000, v97
	v_lshl_add_u64 v[108:109], v[108:109], 0, v[132:133]
	v_lshlrev_b32_e32 v110, 16, v111
	v_and_b32_e32 v111, 0xffff0000, v111
	v_lshlrev_b32_e32 v120, 16, v121
	v_and_b32_e32 v121, 0xffff0000, v121
	v_pk_fma_f32 v[78:79], v[78:79], v[118:119], v[96:97]
	v_pk_fma_f32 v[76:77], v[76:77], v[116:117], v[98:99]
	v_pk_fma_f32 v[74:75], v[74:75], v[114:115], v[120:121]
	v_pk_fma_f32 v[72:73], v[72:73], v[112:113], v[110:111]
	global_store_dwordx4 v[108:109], v[76:79], off
	global_store_dwordx4 v[108:109], v[72:75], off offset:64
	v_add_u32_e32 v96, 0xb0, v188
	v_ashrrev_i32_e32 v97, 31, v96
	v_lshlrev_b64 v[76:77], 11, v[96:97]
	v_lshl_add_u64 v[76:77], v[170:171], 0, v[76:77]
	v_lshl_add_u64 v[98:99], v[76:77], 0, v[136:137]
	v_lshlrev_b64 v[136:137], 10, v[96:97]
	s_waitcnt vmcnt(12)
	s_nop 1
	v_mov_b32_e32 v72, v200
	v_mov_b32_e32 v73, v201
	v_mov_b32_e32 v74, v202
	v_mov_b32_e32 v75, v203
	s_nop 1
	v_permlane16_swap_b32_e32 v72, v74
	v_permlane16_swap_b32_e32 v73, v75
	v_lshlrev_b32_e32 v76, 16, v72
	v_and_b32_e32 v77, 0xffff0000, v72
	v_lshlrev_b32_e32 v72, 16, v73
	v_and_b32_e32 v73, 0xffff0000, v73
	v_lshlrev_b32_e32 v110, 16, v74
	v_and_b32_e32 v111, 0xffff0000, v74
	v_lshlrev_b32_e32 v78, 16, v75
	v_and_b32_e32 v79, 0xffff0000, v75
	v_pk_fma_f32 v[74:75], v[102:103], v[94:95], v[72:73]
	v_pk_fma_f32 v[72:73], v[100:101], v[92:93], v[76:77]
	v_pk_fma_f32 v[78:79], v[106:107], v[90:91], v[78:79]
	v_pk_fma_f32 v[76:77], v[104:105], v[88:89], v[110:111]
	global_store_dwordx4 v[108:109], v[72:75], off offset:512
	global_store_dwordx4 v[108:109], v[76:79], off offset:576
	s_waitcnt vmcnt(11)
	s_nop 1
	v_mov_b32_e32 v72, v204
	v_mov_b32_e32 v73, v205
	v_mov_b32_e32 v74, v206
	v_mov_b32_e32 v75, v207
	s_nop 1
	v_mov_b32_e32 v101, v75
	v_mov_b32_e32 v79, v74
	v_lshlrev_b64 v[76:77], 12, v[96:97]
	s_nop 0
	v_permlane16_swap_b32_e32 v72, v79
	v_permlane16_swap_b32_e32 v73, v101
	v_lshl_add_u64 v[76:77], s[0:1], 0, v[76:77]
	v_lshlrev_b32_e32 v74, 16, v72
	v_and_b32_e32 v75, 0xffff0000, v72
	v_lshlrev_b32_e32 v72, 16, v73
	v_and_b32_e32 v73, 0xffff0000, v73
	v_lshl_add_u64 v[76:77], v[76:77], 0, v[132:133]
	v_lshlrev_b32_e32 v78, 16, v79
	v_and_b32_e32 v79, 0xffff0000, v79
	v_lshlrev_b32_e32 v100, 16, v101
	v_and_b32_e32 v101, 0xffff0000, v101
	v_pk_fma_f32 v[70:71], v[70:71], v[118:119], v[72:73]
	v_pk_fma_f32 v[68:69], v[68:69], v[116:117], v[74:75]
	v_pk_fma_f32 v[66:67], v[66:67], v[114:115], v[100:101]
	v_pk_fma_f32 v[64:65], v[64:65], v[112:113], v[78:79]
	global_store_dwordx4 v[76:77], v[68:71], off
	global_store_dwordx4 v[76:77], v[64:67], off offset:64
	s_waitcnt vmcnt(10)
	s_nop 1
	v_mov_b32_e32 v64, v208
	v_mov_b32_e32 v65, v209
	v_mov_b32_e32 v66, v210
	v_mov_b32_e32 v67, v211
	s_nop 1
	v_permlane16_swap_b32_e32 v64, v66
	v_permlane16_swap_b32_e32 v65, v67
	v_lshlrev_b32_e32 v68, 16, v64
	v_and_b32_e32 v69, 0xffff0000, v64
	v_lshlrev_b32_e32 v64, 16, v65
	v_and_b32_e32 v65, 0xffff0000, v65
	v_lshlrev_b32_e32 v70, 16, v66
	v_and_b32_e32 v71, 0xffff0000, v66
	v_lshlrev_b32_e32 v72, 16, v67
	v_and_b32_e32 v73, 0xffff0000, v67
	v_pk_fma_f32 v[66:67], v[86:87], v[94:95], v[64:65]
	v_pk_fma_f32 v[64:65], v[84:85], v[92:93], v[68:69]
	v_pk_fma_f32 v[130:131], v[82:83], v[90:91], v[72:73]
	v_pk_fma_f32 v[128:129], v[80:81], v[88:89], v[70:71]
	global_store_dwordx4 v[76:77], v[64:67], off offset:512
